# diff attention PV segment: five plain v_pk_add_f32 split into scalar v_add_f32 pairs (bit-identical)
# baseline (speedup 1.0000x reference)
; __device__ __forceinline__ s16x4 vtr(const ALDS unsigned char* p) { return __builtin_bit_cast(s16x4, __builtin_amdgcn_ds_read_tr16_b64_v4i16((ALDS s16x4*)p)); }
; template <int DV, bool BAND> ...
;     ...
;         ATT_EXP_SLICE(p0, 0, pfs[0]);
; #pragma unroll
;         for (int ks = 0; ks < 4; ++ks) {
;             if (ks + 1 < 4) {
; #pragma unroll
;                 for (int db = 0; db < NDB; ++db) { vlo[(ks + 1) & 1][db] = vtr(sb + va[db] + (ks + 1) * (16 * ROWB)); vhh[(ks + 1) & 1][db] = vtr(sb + va[db] + (ks + 1) * (16 * ROWB) + 4 * ROWB); }
;             }
; #pragma unroll
;             for (int db = 0; db < NDB; ++db) {
;                 const s16x4 lo = vlo[ks & 1][db], hh = vhh[ks & 1][db];
;                 const bf16x8 vf = (bf16x8){lo[0], lo[1], lo[2], lo[3], hh[0], hh[1], hh[2], hh[3]};
;                 o[db] = __builtin_amdgcn_mfma_f32_32x32x16_bf16(vf, pfs[ks], o[db], 0, 0, 0);
;             }
;             if (ks == 0) ATT_EXP_SLICE(p0, 8, pfs[1]);
;             if (ks == 1) ATT_EXP_SLICE(p1, 0, pfs[2]);
;             if (ks == 2) ATT_EXP_SLICE(p1, 8, pfs[3]);
;         }
;     ...
;         l += ssum;
;         s_cur = (s_cur == 2 * SLOT) ? 0 : s_cur + SLOT; s_n2 = (s_n2 == 2 * SLOT) ? 0 : s_n2 + SLOT;
.Ldiff_b2_nowait:
	s_barrier
	s_setprio 0
	v_exp_f32_e32 v167, v98
	v_exp_f32_e32 v169, v99
	v_exp_f32_e32 v171, v100
	v_exp_f32_e32 v173, v101
	v_exp_f32_e32 v166, v102
	v_exp_f32_e32 v168, v103
	v_exp_f32_e32 v170, v104
	v_exp_f32_e32 v172, v105
	v_cvt_pk_bf16_f32 v98, v167, v169
	v_cvt_pk_bf16_f32 v99, v171, v173
	v_cvt_pk_bf16_f32 v100, v166, v168
	v_cvt_pk_bf16_f32 v101, v170, v172
	ds_read_b64_tr_b16 v[102:103], v164 offset:20480
	ds_read_b64_tr_b16 v[104:105], v164 offset:21504
	s_waitcnt lgkmcnt(8)
	v_mfma_f32_32x32x16_bf16 v[50:65], v[142:145], v[98:101], v[50:65]
	v_exp_f32_e32 v142, v82
	v_exp_f32_e32 v143, v83
	v_exp_f32_e32 v144, v84
	v_exp_f32_e32 v145, v85
	v_exp_f32_e32 v165, v86
	v_exp_f32_e32 v174, v87
	v_exp_f32_e32 v175, v88
	s_waitcnt lgkmcnt(6)
	v_mfma_f32_32x32x16_bf16 v[34:49], v[138:141], v[98:101], v[34:49]
	v_exp_f32_e32 v139, v110
	v_exp_f32_e32 v141, v111
	v_exp_f32_e32 v138, v112
	v_exp_f32_e32 v140, v113
	v_exp_f32_e32 v176, v89
	v_cvt_pk_bf16_f32 v86, v142, v143
	v_cvt_pk_bf16_f32 v87, v144, v145
	s_waitcnt lgkmcnt(4)
	v_mfma_f32_32x32x16_bf16 v[18:33], v[134:137], v[98:101], v[18:33]
	v_exp_f32_e32 v135, v106
	v_exp_f32_e32 v137, v107
	v_exp_f32_e32 v134, v108
	v_exp_f32_e32 v136, v109
	ds_read_b64_tr_b16 v[106:107], v164 offset:24576
	ds_read_b64_tr_b16 v[108:109], v164 offset:25600
	v_cvt_pk_bf16_f32 v88, v165, v174
	v_cvt_pk_bf16_f32 v89, v175, v176
	s_waitcnt lgkmcnt(4)
	v_mfma_f32_32x32x16_bf16 v[2:17], v[130:133], v[98:101], v[2:17]
	v_cvt_pk_bf16_f32 v98, v135, v137
	v_cvt_pk_bf16_f32 v99, v134, v136
	v_cvt_pk_bf16_f32 v100, v139, v141
	v_cvt_pk_bf16_f32 v101, v138, v140
	v_add_f32_e64 v82, v168, v166
	v_add_f32_e64 v83, v169, v167
	v_exp_f32_e32 v0, v90
	v_exp_f32_e32 v90, v94
	s_waitcnt lgkmcnt(2)
	v_mfma_f32_32x32x16_bf16 v[50:65], v[102:105], v[98:101], v[50:65]
	ds_read_b64_tr_b16 v[102:103], v163 offset:4096
	ds_read_b64_tr_b16 v[104:105], v163 offset:5120
	ds_read_b64_tr_b16 v[110:111], v164 offset:29696
	v_exp_f32_e32 v94, v96
	v_exp_f32_e32 v96, v97
	v_add_f32_e32 v97, v176, v175
	s_add_i32 s7, s6, 0x8000
	s_cmp_lg_u32 s6, 0x18000
	s_cselect_b32 s6, s7, 0
	s_waitcnt lgkmcnt(1)
	v_mfma_f32_32x32x16_bf16 v[34:49], v[102:105], v[98:101], v[34:49]
	ds_read_b64_tr_b16 v[102:103], v161 offset:4096
	ds_read_b64_tr_b16 v[104:105], v161 offset:5120
	ds_read_b64_tr_b16 v[130:131], v161 offset:8192
	ds_read_b64_tr_b16 v[132:133], v161 offset:9216
	s_add_i32 s7, s5, 0x8000
	s_cmp_lg_u32 s5, 0x18000
	s_cselect_b32 s5, s7, 0
	s_add_i32 s4, s4, 1
	s_cmp_lg_u32 s4, 64
	s_waitcnt lgkmcnt(2)
	v_mfma_f32_32x32x16_bf16 v[18:33], v[102:105], v[98:101], v[18:33]
	ds_read_b64_tr_b16 v[102:103], v162 offset:4096
	ds_read_b64_tr_b16 v[104:105], v162 offset:5120
	ds_read_b64_tr_b16 v[84:85], v161 offset:13312
	s_waitcnt lgkmcnt(1)
	v_mfma_f32_32x32x16_bf16 v[2:17], v[102:105], v[98:101], v[2:17]
	v_add_f32_e64 v102, v172, v170
	v_add_f32_e64 v103, v173, v171
	v_add_f32_e64 v82, v102, v82
	v_add_f32_e64 v83, v103, v83
	v_mfma_f32_32x32x16_bf16 v[50:65], v[106:109], v[86:89], v[50:65]
	ds_read_b64_tr_b16 v[98:99], v163 offset:8192
	ds_read_b64_tr_b16 v[100:101], v163 offset:9216
	ds_read_b64_tr_b16 v[108:109], v164 offset:28672
	ds_read_b64_tr_b16 v[102:103], v163 offset:12288
	ds_read_b64_tr_b16 v[104:105], v163 offset:13312
	v_pk_add_f32 v[106:107], v[82:83], v[82:83] op_sel_hi:[0,1]
	v_add_f32_e32 v82, v136, v134
	v_add_f32_e32 v83, v137, v135
	v_exp_f32_e32 v106, v91
	v_pk_add_f32 v[112:113], v[82:83], v[82:83] op_sel_hi:[0,1]
	v_add_f32_e32 v82, v140, v138
	v_add_f32_e32 v83, v141, v139
	s_waitcnt lgkmcnt(3)
	v_mfma_f32_32x32x16_bf16 v[34:49], v[98:101], v[86:89], v[34:49]
	ds_read_b64_tr_b16 v[98:99], v162 offset:8192
	ds_read_b64_tr_b16 v[100:101], v162 offset:9216
	v_add_f32_e64 v134, v82, v82
	v_add_f32_e64 v135, v82, v83
	v_exp_f32_e32 v112, v92
	v_exp_f32_e32 v134, v93
	v_exp_f32_e32 v92, v95
	v_add_f32_e32 v91, v143, v142
	v_add_f32_e32 v93, v145, v144
	v_mfma_f32_32x32x16_bf16 v[18:33], v[130:133], v[86:89], v[18:33]
	ds_read_b64_tr_b16 v[130:131], v162 offset:12288
	ds_read_b64_tr_b16 v[132:133], v162 offset:13312
	ds_read_b64_tr_b16 v[82:83], v161 offset:12288
	v_add_f32_e32 v95, v174, v165
	s_waitcnt lgkmcnt(3)
	v_mfma_f32_32x32x16_bf16 v[2:17], v[98:101], v[86:89], v[2:17]
	v_cvt_pk_bf16_f32 v86, v0, v106
	v_cvt_pk_bf16_f32 v87, v112, v134
	v_cvt_pk_bf16_f32 v88, v90, v92
	v_cvt_pk_bf16_f32 v89, v94, v96
	v_add_f32_e64 v98, v106, v0
	v_add_f32_e64 v99, v107, v1
	v_add_f32_e32 v100, v134, v112
	v_add_f32_e32 v101, v135, v113
	v_add_f32_e32 v90, v92, v90
	v_add_f32_e32 v91, v93, v91
	v_mfma_f32_32x32x16_bf16 v[50:65], v[108:111], v[86:89], v[50:65]
	v_add_f32_e64 v92, v96, v94
	v_add_f32_e64 v93, v97, v95
	v_add_f32_e64 v98, v100, v98
	v_add_f32_e64 v99, v101, v99
	v_add_f32_e64 v90, v92, v90
	v_add_f32_e64 v91, v93, v91
	v_add_f32_e32 v90, v90, v98
	v_add_f32_e32 v91, v91, v99
	s_nop 0
	v_add_f32_e32 v0, v90, v91
	v_mfma_f32_32x32x16_bf16 v[34:49], v[102:105], v[86:89], v[34:49]
	v_add_f32_e32 v160, v160, v0
	s_waitcnt lgkmcnt(0)
	v_mfma_f32_32x32x16_bf16 v[18:33], v[82:85], v[86:89], v[18:33]
	v_mfma_f32_32x32x16_bf16 v[2:17], v[130:133], v[86:89], v[2:17]
	s_cbranch_scc0 .LBB0_777
